# attention: first 8 V^T fragment reads of PV hoisted above the B2 barrier (cross-segment overlap)
# baseline (speedup 1.0000x reference)
.LBB0_68:
	v_pk_add_f32 v[156:157], v[156:157], 0 op_sel_hi:[1,0]
	v_pk_add_f32 v[102:103], v[102:103], v[152:153] op_sel_hi:[1,0] neg_lo:[0,1] neg_hi:[0,1]
	v_pk_add_f32 v[156:157], v[158:159], v[156:157]
	v_pk_add_f32 v[104:105], v[104:105], v[152:153] op_sel_hi:[1,0] neg_lo:[0,1] neg_hi:[0,1]
	v_pk_add_f32 v[156:157], v[160:161], v[156:157]
	v_exp_f32_e32 v102, v102
	v_pk_add_f32 v[156:157], v[162:163], v[156:157]
	v_exp_f32_e32 v103, v103
	v_pk_add_f32 v[110:111], v[110:111], v[156:157]
	v_exp_f32_e32 v104, v104
	v_pk_add_f32 v[110:111], v[112:113], v[110:111]
	v_exp_f32_e32 v105, v105
	v_pk_add_f32 v[106:107], v[106:107], v[110:111]
	v_pk_add_f32 v[98:99], v[98:99], v[152:153] op_sel_hi:[1,0] neg_lo:[0,1] neg_hi:[0,1]
	v_pk_add_f32 v[106:107], v[108:109], v[106:107]
	v_pk_add_f32 v[100:101], v[100:101], v[152:153] op_sel_hi:[1,0] neg_lo:[0,1] neg_hi:[0,1]
	v_exp_f32_e32 v98, v98
	v_exp_f32_e32 v99, v99
	v_add_f32_e32 v106, v106, v107
	v_exp_f32_e32 v100, v100
	v_exp_f32_e32 v101, v101
	v_pk_add_f32 v[14:15], v[14:15], v[152:153] op_sel_hi:[1,0] neg_lo:[0,1] neg_hi:[0,1]
	v_add_f32_e32 v115, v115, v106
	v_pk_add_f32 v[106:107], v[102:103], 0 op_sel_hi:[1,0]
	v_pk_add_f32 v[16:17], v[16:17], v[152:153] op_sel_hi:[1,0] neg_lo:[0,1] neg_hi:[0,1]
	v_exp_f32_e32 v14, v14
	v_exp_f32_e32 v15, v15
	v_pk_add_f32 v[106:107], v[104:105], v[106:107]
	v_exp_f32_e32 v16, v16
	v_exp_f32_e32 v17, v17
	v_pk_add_f32 v[10:11], v[10:11], v[152:153] op_sel_hi:[1,0] neg_lo:[0,1] neg_hi:[0,1]
	v_pk_add_f32 v[106:107], v[98:99], v[106:107]
	v_pk_add_f32 v[12:13], v[12:13], v[152:153] op_sel_hi:[1,0] neg_lo:[0,1] neg_hi:[0,1]
	v_exp_f32_e32 v108, v10
	v_exp_f32_e32 v109, v11
	v_pk_add_f32 v[106:107], v[100:101], v[106:107]
	v_exp_f32_e32 v110, v12
	v_exp_f32_e32 v111, v13
	v_pk_add_f32 v[10:11], v[14:15], v[106:107]
	s_nop 0
	v_pk_add_f32 v[10:11], v[16:17], v[10:11]
	s_nop 0
	v_pk_add_f32 v[10:11], v[108:109], v[10:11]
	s_nop 0
	v_pk_add_f32 v[10:11], v[110:111], v[10:11]
	s_nop 0
	v_add_f32_e32 v10, v10, v11
	v_add_f32_e32 v138, v138, v10
	v_cvt_pk_bf16_f32 v10, v102, v103
	v_cvt_pk_bf16_f32 v11, v104, v105
	v_cvt_pk_bf16_f32 v12, v98, v99
	v_cvt_pk_bf16_f32 v13, v100, v101
	v_cvt_pk_bf16_f32 v14, v14, v15
	v_cvt_pk_bf16_f32 v15, v16, v17
	v_cvt_pk_bf16_f32 v16, v108, v109
	v_cvt_pk_bf16_f32 v17, v110, v111
	s_and_b32 s25, s19, 0x18000
	s_add_i32 s25, s64, s25
	v_add_u32_e32 v102, s25, v149
	v_add_u32_e32 v185, s25, v180
	ds_read_b128 v[188:191], v102 offset:16384
	ds_read_b128 v[192:195], v102 offset:18432
	ds_read_b128 v[196:199], v102 offset:20480
	ds_read_b128 v[200:203], v102 offset:22528
	ds_read_b128 v[204:207], v102 offset:24576
	ds_read_b128 v[208:211], v102 offset:26624
	ds_read_b128 v[212:215], v102 offset:28672
	ds_read_b128 v[216:219], v102 offset:30720

.LBB0_74:
	s_waitcnt lgkmcnt(0)
	s_barrier
	s_and_b64 vcc, exec, s[8:9]
	s_cbranch_vccnz .LBB0_60
	s_waitcnt lgkmcnt(7)
	v_mfma_f32_16x16x32_bf16 v[78:81], v[188:191], v[2:5], v[78:81]
	v_mfma_f32_16x16x32_bf16 v[46:49], v[188:191], v[10:13], v[46:49]
	ds_read_b128 v[188:191], v185 offset:16384
	s_waitcnt lgkmcnt(7)
	v_mfma_f32_16x16x32_bf16 v[74:77], v[192:195], v[2:5], v[74:77]
	v_mfma_f32_16x16x32_bf16 v[42:45], v[192:195], v[10:13], v[42:45]
	ds_read_b128 v[192:195], v185 offset:18432
	s_waitcnt lgkmcnt(7)
	v_mfma_f32_16x16x32_bf16 v[70:73], v[196:199], v[2:5], v[70:73]
	v_mfma_f32_16x16x32_bf16 v[38:41], v[196:199], v[10:13], v[38:41]
	ds_read_b128 v[196:199], v185 offset:20480
	s_waitcnt lgkmcnt(7)
	v_mfma_f32_16x16x32_bf16 v[66:69], v[200:203], v[2:5], v[66:69]
	v_mfma_f32_16x16x32_bf16 v[34:37], v[200:203], v[10:13], v[34:37]
	ds_read_b128 v[200:203], v185 offset:22528
	s_waitcnt lgkmcnt(7)
	v_mfma_f32_16x16x32_bf16 v[62:65], v[204:207], v[2:5], v[62:65]
	v_mfma_f32_16x16x32_bf16 v[30:33], v[204:207], v[10:13], v[30:33]
	ds_read_b128 v[204:207], v185 offset:24576
	s_waitcnt lgkmcnt(7)
	v_mfma_f32_16x16x32_bf16 v[58:61], v[208:211], v[2:5], v[58:61]
	v_mfma_f32_16x16x32_bf16 v[26:29], v[208:211], v[10:13], v[26:29]
	ds_read_b128 v[208:211], v185 offset:26624
	s_waitcnt lgkmcnt(7)
	v_mfma_f32_16x16x32_bf16 v[54:57], v[212:215], v[2:5], v[54:57]
	v_mfma_f32_16x16x32_bf16 v[22:25], v[212:215], v[10:13], v[22:25]
	ds_read_b128 v[212:215], v185 offset:28672
	s_waitcnt lgkmcnt(7)
	v_mfma_f32_16x16x32_bf16 v[50:53], v[216:219], v[2:5], v[50:53]
	v_mfma_f32_16x16x32_bf16 v[18:21], v[216:219], v[10:13], v[18:21]
	ds_read_b128 v[216:219], v185 offset:30720
	s_waitcnt lgkmcnt(7)
	v_mfma_f32_16x16x32_bf16 v[78:81], v[188:191], v[6:9], v[78:81]
	v_mfma_f32_16x16x32_bf16 v[46:49], v[188:191], v[14:17], v[46:49]
	s_waitcnt lgkmcnt(6)
	v_mfma_f32_16x16x32_bf16 v[74:77], v[192:195], v[6:9], v[74:77]
	v_mfma_f32_16x16x32_bf16 v[42:45], v[192:195], v[14:17], v[42:45]
	s_waitcnt lgkmcnt(5)
	v_mfma_f32_16x16x32_bf16 v[70:73], v[196:199], v[6:9], v[70:73]
	v_mfma_f32_16x16x32_bf16 v[38:41], v[196:199], v[14:17], v[38:41]
	s_waitcnt lgkmcnt(4)
	v_mfma_f32_16x16x32_bf16 v[66:69], v[200:203], v[6:9], v[66:69]
	v_mfma_f32_16x16x32_bf16 v[34:37], v[200:203], v[14:17], v[34:37]
	s_waitcnt lgkmcnt(3)
	v_mfma_f32_16x16x32_bf16 v[62:65], v[204:207], v[6:9], v[62:65]
	v_mfma_f32_16x16x32_bf16 v[30:33], v[204:207], v[14:17], v[30:33]
	s_waitcnt lgkmcnt(2)
	v_mfma_f32_16x16x32_bf16 v[58:61], v[208:211], v[6:9], v[58:61]
	v_mfma_f32_16x16x32_bf16 v[26:29], v[208:211], v[14:17], v[26:29]
	s_waitcnt lgkmcnt(1)
	v_mfma_f32_16x16x32_bf16 v[54:57], v[212:215], v[6:9], v[54:57]
	v_mfma_f32_16x16x32_bf16 v[22:25], v[212:215], v[14:17], v[22:25]
	s_waitcnt lgkmcnt(0)
	v_mfma_f32_16x16x32_bf16 v[50:53], v[216:219], v[6:9], v[50:53]
	v_mfma_f32_16x16x32_bf16 v[18:21], v[216:219], v[14:17], v[18:21]
	s_branch .LBB0_60
